# adaLN partial items permuted so a workgroup's waves read adjacent column groups of the same rows
# baseline (speedup 1.0000x reference)
.LBB0_53:
	s_andn2_saveexec_b64 s[30:31], s[6:7]
	s_cbranch_execz .LBB0_8
	v_cmp_lt_u32_e32 vcc, 0x2ff, v110
	v_mov_b32_e32 v1, 0x300
	s_nop 1
	v_cndmask_b32_e32 v0, 0, v1, vcc
	v_sub_u32_e32 v1, v110, v0
	v_mul_u32_u24_e32 v8, 0x2ab, v1
	v_lshrrev_b32_e32 v8, 16, v8
	v_mul_u32_u24_e32 v25, 0x60, v8
	v_sub_u32_e32 v1, v1, v25
	v_lshl_add_u32 v1, v1, 3, v8
	v_add_u32_e32 v0, v0, v1
	v_accvgpr_write_b32 a70, v0
	s_mov_b32 s0, 0x2aaaaaab
	s_nop 0
	v_accvgpr_read_b32 v0, a70
	v_mul_hi_i32 v0, v0, s0
	v_lshrrev_b32_e32 v1, 31, v0
	v_ashrrev_i32_e32 v0, 7, v0
	v_add_u32_e32 v25, v0, v1
	v_mul_i32_i24_e32 v0, 0x300, v25
	v_accvgpr_read_b32 v8, a70
	v_sub_u32_e32 v8, v8, v0
	v_and_b32_e32 v41, 7, v8
	v_readlane_b32 s4, v126, 15
	v_lshl_or_b32 v26, v41, 9, v90
	v_readlane_b32 s14, v126, 25
	v_readlane_b32 s15, v126, 26
	v_readlane_b32 s16, v126, 27
	v_readlane_b32 s17, v126, 28
	v_lshl_add_u64 v[0:1], s[14:15], 0, v[26:27]
	v_add_co_u32_e32 v2, vcc, s84, v0
	s_mov_b32 s0, 0x1800000
	s_nop 0
	v_addc_co_u32_e32 v3, vcc, 0, v1, vcc
	global_load_dword v9, v26, s[16:17]
	global_load_dword v10, v26, s[16:17] offset:256
	global_load_dword v11, v26, s[14:15] offset:256
	global_load_dword v12, v[2:3], off offset:-4096
	global_load_dword v13, v[2:3], off
	global_load_dword v14, v[2:3], off offset:256
	global_load_dword v15, v26, s[14:15]
	v_add_co_u32_e32 v2, vcc, s2, v0
	v_mov_b32_e32 v43, 0
	s_nop 0
	v_addc_co_u32_e32 v3, vcc, 0, v1, vcc
	v_add_co_u32_e32 v0, vcc, s85, v0
	global_load_dword v16, v[2:3], off offset:256
	s_nop 0
	v_addc_co_u32_e32 v1, vcc, 0, v1, vcc
	global_load_dword v17, v[0:1], off
	s_nop 0
	global_load_dword v1, v[0:1], off offset:256
	v_accvgpr_read_b32 v3, a70
	v_and_b32_e32 v3, 7, v3
	v_mul_hi_u32_u24_e32 v5, 0x300000, v3
	v_mul_u32_u24_e32 v4, 0x300000, v3
	v_mad_i64_i32 v[6:7], s[0:1], v25, s0, v[4:5]
	v_lshlrev_b32_e32 v4, 3, v8
	v_and_b32_e32 v4, 0xffffffc0, v4
	v_or_b32_e32 v4, v83, v4
	v_ashrrev_i32_e32 v5, 31, v4
	v_lshl_add_u64 v[6:7], v[4:5], 2, v[6:7]
	s_mov_b32 s33, 0
	v_mov_b32_e32 v2, 0
	v_mov_b32_e32 v0, 0
	v_mov_b32_e32 v3, v43
	v_lshl_add_u64 v[6:7], s[90:91], 0, v[6:7]
	v_readlane_b32 s5, v126, 16
	v_readlane_b32 s6, v126, 17
	v_readlane_b32 s7, v126, 18
	v_readlane_b32 s8, v126, 19
	v_readlane_b32 s9, v126, 20
	v_readlane_b32 s10, v126, 21
	v_readlane_b32 s11, v126, 22
	v_readlane_b32 s12, v126, 23
	v_readlane_b32 s13, v126, 24
	v_readlane_b32 s18, v126, 29
	v_readlane_b32 s19, v126, 30
	s_waitcnt vmcnt(9)
	v_mul_f32_e32 v8, 0xbfb8aa3b, v9
	s_waitcnt vmcnt(8)
	v_mul_f32_e32 v18, 0xbfb8aa3b, v10
	s_waitcnt vmcnt(7)
	v_mul_f32_e32 v19, 0xbfb8aa3b, v11
	s_waitcnt vmcnt(6)
	v_mul_f32_e32 v21, 0xbfb8aa3b, v12
	s_waitcnt vmcnt(5)
	v_mul_f32_e32 v23, 0xbfb8aa3b, v13
	s_waitcnt vmcnt(4)
	v_mul_f32_e32 v24, 0xbfb8aa3b, v14
	s_waitcnt vmcnt(3)
	v_mul_f32_e32 v20, 0xbfb8aa3b, v15
	v_exp_f32_e32 v8, v8
	v_exp_f32_e32 v18, v18
	v_exp_f32_e32 v19, v19
	v_exp_f32_e32 v20, v20
	v_exp_f32_e32 v21, v21
	v_exp_f32_e32 v23, v23
	v_exp_f32_e32 v24, v24
	s_waitcnt vmcnt(2)
	v_mul_f32_e32 v22, 0xbfb8aa3b, v16
	v_exp_f32_e32 v22, v22
	s_waitcnt vmcnt(1)
	v_mul_f32_e32 v26, 0xbfb8aa3b, v17
	s_waitcnt vmcnt(0)
	v_mul_f32_e32 v30, 0xbfb8aa3b, v1
	v_exp_f32_e32 v26, v26
	v_exp_f32_e32 v30, v30
	v_add_f32_e32 v8, 1.0, v8
	v_add_f32_e32 v18, 1.0, v18
	v_add_f32_e32 v19, 1.0, v19
	v_add_f32_e32 v20, 1.0, v20
	v_add_f32_e32 v21, 1.0, v21
	v_add_f32_e32 v22, 1.0, v22
	v_add_f32_e32 v23, 1.0, v23
	v_add_f32_e32 v24, 1.0, v24
	v_add_f32_e32 v26, 1.0, v26
	v_add_f32_e32 v30, 1.0, v30
	v_rcp_f32_e32 v8, v8
	v_rcp_f32_e32 v18, v18
	v_rcp_f32_e32 v19, v19
	v_rcp_f32_e32 v20, v20
	v_rcp_f32_e32 v21, v21
	v_rcp_f32_e32 v22, v22
	v_rcp_f32_e32 v23, v23
	v_rcp_f32_e32 v24, v24
	v_rcp_f32_e32 v26, v26
	v_rcp_f32_e32 v30, v30
	v_mul_f32_e32 v45, v9, v8
	v_mul_f32_e32 v47, v10, v18
	v_mul_f32_e32 v49, v11, v19
	v_mul_f32_e32 v51, v15, v20
	v_mul_f32_e32 v53, v12, v21
	v_mul_f32_e32 v55, v16, v22
	v_mul_f32_e32 v57, v13, v23
	v_mul_f32_e32 v59, v14, v24
	v_mul_f32_e32 v71, v17, v26
	v_mul_f32_e32 v88, v1, v30
	v_mov_b32_e32 v1, v43
